# F14 + fmix: warm-up touch of the unit's 32 loop-invariant twiddle gathers behind the stage-V loads (L1 prefetch)
# speedup vs baseline: 1.0084x; 1.0000x over previous
.LBB1_480:
	s_ashr_i32 s1, s26, 7
	s_and_b32 s5, s27, 0x1fc
	s_lshl_b32 s6, s1, 9
	s_or_b32 s16, s6, s5
	s_ashr_i32 s17, s16, 31
	s_lshl_b64 s[6:7], s[16:17], 14
	s_add_u32 s6, s10, s6
	s_addc_u32 s7, s11, s7
	v_lshl_add_u64 v[0:1], s[6:7], 0, v[112:113]
	v_lshl_add_u64 v[4:5], v[0:1], 0, s[38:39]
	s_waitcnt vmcnt(0) lgkmcnt(0)
	s_barrier
	global_load_dwordx4 v[172:175], v[4:5], off
	v_add_co_u32_e32 v0, vcc, s75, v4
	s_nop 1
	v_addc_co_u32_e32 v1, vcc, 0, v5, vcc
	global_load_dwordx4 v[8:11], v[0:1], off
	s_or_b32 s6, s16, 1
	s_ashr_i32 s7, s6, 31
	s_lshl_b64 s[6:7], s[6:7], 14
	s_add_u32 s6, s10, s6
	s_addc_u32 s7, s11, s7
	v_lshl_add_u64 v[0:1], s[6:7], 0, v[112:113]
	v_lshl_add_u64 v[4:5], v[0:1], 0, s[38:39]
	global_load_dwordx4 v[12:15], v[4:5], off
	v_add_co_u32_e32 v0, vcc, s75, v4
	s_nop 1
	v_addc_co_u32_e32 v1, vcc, 0, v5, vcc
	global_load_dwordx4 v[18:21], v[0:1], off
	s_or_b32 s6, s16, 2
	s_ashr_i32 s7, s6, 31
	s_lshl_b64 s[6:7], s[6:7], 14
	s_add_u32 s6, s10, s6
	s_addc_u32 s7, s11, s7
	v_lshl_add_u64 v[0:1], s[6:7], 0, v[112:113]
	v_lshl_add_u64 v[4:5], v[0:1], 0, s[38:39]
	global_load_dwordx4 v[22:25], v[4:5], off
	v_add_co_u32_e32 v0, vcc, s75, v4
	s_nop 1
	v_addc_co_u32_e32 v1, vcc, 0, v5, vcc
	global_load_dwordx4 v[26:29], v[0:1], off
	s_or_b32 s6, s16, 3
	s_ashr_i32 s7, s6, 31
	s_lshl_b64 s[6:7], s[6:7], 14
	s_add_u32 s6, s10, s6
	s_addc_u32 s7, s11, s7
	v_lshl_add_u64 v[0:1], s[6:7], 0, v[112:113]
	v_lshl_add_u64 v[4:5], v[0:1], 0, s[38:39]
	global_load_dwordx4 v[30:33], v[4:5], off
	v_add_co_u32_e32 v0, vcc, s75, v4
	s_nop 1
	v_addc_co_u32_e32 v1, vcc, 0, v5, vcc
	global_load_dwordx4 v[168:171], v[0:1], off
	global_load_dword v192, v[64:65], off
	global_load_dword v192, v[66:67], off
	global_load_dword v192, v[68:69], off
	global_load_dword v192, v[70:71], off
	global_load_dword v192, v[72:73], off
	global_load_dword v192, v[74:75], off
	global_load_dword v192, v[76:77], off
	global_load_dword v192, v[78:79], off
	global_load_dword v192, v[80:81], off
	global_load_dword v192, v[82:83], off
	global_load_dword v192, v[84:85], off
	global_load_dword v192, v[86:87], off
	global_load_dword v192, v[88:89], off
	global_load_dword v192, v[90:91], off
	global_load_dword v192, v[92:93], off
	global_load_dword v192, v[94:95], off
	global_load_dword v192, v[96:97], off
	global_load_dword v192, v[98:99], off
	global_load_dword v192, v[100:101], off
	global_load_dword v192, v[102:103], off
	global_load_dword v192, v[104:105], off
	global_load_dword v192, v[106:107], off
	global_load_dword v192, v[108:109], off
	global_load_dword v192, v[110:111], off
	global_load_dword v192, v[114:115], off
	global_load_dword v192, v[116:117], off
	global_load_dword v192, v[118:119], off
	global_load_dword v192, v[120:121], off
	global_load_dword v192, v[122:123], off
	global_load_dword v192, v[124:125], off
	global_load_dword v192, v[126:127], off
	global_load_dword v192, v[128:129], off
	s_lshl_b32 s1, s1, 12
	s_lshl_b32 s5, s5, 1
	s_add_u32 s16, s24, s5
	s_addc_u32 s17, s25, 0
	s_add_i32 s26, s26, s33
	s_add_i32 s27, s27, s9
	s_cmpk_lt_i32 s26, 0x100
	v_add_u32_e32 v6, s18, v131
	v_add_u32_e32 v16, v132, v134
	v_add_u32_e32 v17, v133, v135
	s_waitcnt vmcnt(39)
	ds_write_b16 v6, v172 offset:55296
	ds_write_b16_d16_hi v6, v172 offset:55584
	ds_write_b16 v6, v173 offset:55872
	ds_write_b16_d16_hi v6, v173 offset:56160
	ds_write_b16 v6, v174 offset:56448
	ds_write_b16_d16_hi v6, v174 offset:56736
	ds_write_b16 v6, v175 offset:57024
	ds_write_b16_d16_hi v6, v175 offset:57312
	s_waitcnt vmcnt(38)
	ds_write_b16 v6, v8 offset:55424
	ds_write_b16_d16_hi v6, v8 offset:55712
	ds_write_b16 v6, v9 offset:56000
	ds_write_b16_d16_hi v6, v9 offset:56288
	ds_write_b16 v6, v10 offset:56576
	ds_write_b16_d16_hi v6, v10 offset:56864
	ds_write_b16 v6, v11 offset:57152
	ds_write_b16_d16_hi v6, v11 offset:57440
	v_add_u32_e32 v6, s19, v131
	s_waitcnt vmcnt(37)
	ds_write_b16 v6, v12 offset:18432
	ds_write_b16_d16_hi v6, v12 offset:18720
	ds_write_b16 v6, v13 offset:19008
	ds_write_b16_d16_hi v6, v13 offset:19296
	ds_write_b16 v6, v14 offset:19584
	ds_write_b16_d16_hi v6, v14 offset:19872
	ds_write_b16 v6, v15 offset:20160
	ds_write_b16_d16_hi v6, v15 offset:20448
	s_waitcnt vmcnt(36)
	ds_write_b16 v6, v18 offset:18560
	ds_write_b16_d16_hi v6, v18 offset:18848
	ds_write_b16 v6, v19 offset:19136
	ds_write_b16_d16_hi v6, v19 offset:19424
	ds_write_b16 v6, v20 offset:19712
	ds_write_b16_d16_hi v6, v20 offset:20000
	ds_write_b16 v6, v21 offset:20288
	ds_write_b16_d16_hi v6, v21 offset:20576
	s_waitcnt vmcnt(35)
	ds_write_b16 v6, v22 offset:36864
	ds_write_b16_d16_hi v6, v22 offset:37152
	ds_write_b16 v6, v23 offset:37440
	ds_write_b16_d16_hi v6, v23 offset:37728
	ds_write_b16 v6, v24 offset:38016
	ds_write_b16_d16_hi v6, v24 offset:38304
	ds_write_b16 v6, v25 offset:38592
	ds_write_b16_d16_hi v6, v25 offset:38880
	s_waitcnt vmcnt(34)
	ds_write_b16 v6, v26 offset:36992
	ds_write_b16_d16_hi v6, v26 offset:37280
	ds_write_b16 v6, v27 offset:37568
	ds_write_b16_d16_hi v6, v27 offset:37856
	ds_write_b16 v6, v28 offset:38144
	ds_write_b16_d16_hi v6, v28 offset:38432
	ds_write_b16 v6, v29 offset:38720
	ds_write_b16_d16_hi v6, v29 offset:39008
	s_waitcnt vmcnt(33)
	ds_write_b16 v6, v30 offset:55296
	ds_write_b16_d16_hi v6, v30 offset:55584
	ds_write_b16 v6, v31 offset:55872
	ds_write_b16_d16_hi v6, v31 offset:56160
	ds_write_b16 v6, v32 offset:56448
	ds_write_b16_d16_hi v6, v32 offset:56736
	ds_write_b16 v6, v33 offset:57024
	ds_write_b16_d16_hi v6, v33 offset:57312
	s_waitcnt vmcnt(32)
	ds_write_b16 v6, v168 offset:55424
	ds_write_b16_d16_hi v6, v168 offset:55712
	ds_write_b16 v6, v169 offset:56000
	ds_write_b16_d16_hi v6, v169 offset:56288
	ds_write_b16 v6, v170 offset:56576
	ds_write_b16_d16_hi v6, v170 offset:56864
	ds_write_b16 v6, v171 offset:57152
	ds_write_b16_d16_hi v6, v171 offset:57440
	s_waitcnt lgkmcnt(0)
	s_barrier
	ds_read_b128 v[12:15], v16
	ds_read_b128 v[8:11], v16 offset:4608
	ds_read_b128 v[4:7], v16 offset:18432
	ds_read_b128 v[0:3], v16 offset:23040
	ds_read_b128 v[18:21], v17 offset:55296
	ds_read_b128 v[22:25], v17 offset:59904
	ds_read_b128 v[26:29], v17 offset:64512
	ds_read_b128 v[30:33], v151 offset:64512
	s_waitcnt lgkmcnt(3)
	v_mfma_f32_16x16x32_bf16 v[34:37], v[12:15], v[18:21], 0
	s_waitcnt lgkmcnt(2)
	v_mfma_f32_16x16x32_bf16 v[38:41], v[12:15], v[22:25], 0
	s_waitcnt lgkmcnt(1)
	v_mfma_f32_16x16x32_bf16 v[42:45], v[12:15], v[26:29], 0
	s_waitcnt lgkmcnt(0)
	v_mfma_f32_16x16x32_bf16 v[12:15], v[12:15], v[30:33], 0
	v_mfma_f32_16x16x32_bf16 v[46:49], v[8:11], v[18:21], 0
	v_mfma_f32_16x16x32_bf16 v[50:53], v[8:11], v[22:25], 0
	v_mfma_f32_16x16x32_bf16 v[54:57], v[8:11], v[26:29], 0
	v_mfma_f32_16x16x32_bf16 v[8:11], v[8:11], v[30:33], 0
	v_mfma_f32_16x16x32_bf16 v[58:61], v[4:7], v[18:21], 0
	v_mfma_f32_16x16x32_bf16 v[160:163], v[4:7], v[22:25], 0
	v_mfma_f32_16x16x32_bf16 v[164:167], v[4:7], v[26:29], 0
	v_mfma_f32_16x16x32_bf16 v[4:7], v[4:7], v[30:33], 0
	v_mfma_f32_16x16x32_bf16 v[18:21], v[0:3], v[18:21], 0
	v_mfma_f32_16x16x32_bf16 v[22:25], v[0:3], v[22:25], 0
	v_mfma_f32_16x16x32_bf16 v[26:29], v[0:3], v[26:29], 0
	v_mfma_f32_16x16x32_bf16 v[0:3], v[0:3], v[30:33], 0
	ds_read_b128 v[30:33], v16 offset:64
	ds_read_b128 v[168:171], v16 offset:4672
	ds_read_b128 v[172:175], v16 offset:18496
	ds_read_b128 v[176:179], v16 offset:23104
	ds_read_b128 v[180:183], v17 offset:55360
	ds_read_b128 v[184:187], v17 offset:59968
	ds_read_b128 v[188:191], v17 offset:64576
	ds_read_b128 v[206:209], v151 offset:64576
	s_waitcnt lgkmcnt(3)
	v_mfma_f32_16x16x32_bf16 v[34:37], v[30:33], v[180:183], v[34:37]
	s_waitcnt lgkmcnt(2)
	v_mfma_f32_16x16x32_bf16 v[38:41], v[30:33], v[184:187], v[38:41]
	s_waitcnt lgkmcnt(1)
	v_mfma_f32_16x16x32_bf16 v[42:45], v[30:33], v[188:191], v[42:45]
	s_waitcnt lgkmcnt(0)
	v_mfma_f32_16x16x32_bf16 v[12:15], v[30:33], v[206:209], v[12:15]
	v_mfma_f32_16x16x32_bf16 v[30:33], v[168:171], v[180:183], v[46:49]
	v_mfma_f32_16x16x32_bf16 v[46:49], v[168:171], v[184:187], v[50:53]
	v_mfma_f32_16x16x32_bf16 v[50:53], v[168:171], v[188:191], v[54:57]
	v_mfma_f32_16x16x32_bf16 v[8:11], v[168:171], v[206:209], v[8:11]
	v_mfma_f32_16x16x32_bf16 v[54:57], v[172:175], v[180:183], v[58:61]
	v_mfma_f32_16x16x32_bf16 v[58:61], v[172:175], v[184:187], v[160:163]
	v_mfma_f32_16x16x32_bf16 v[160:163], v[172:175], v[188:191], v[164:167]
	v_mfma_f32_16x16x32_bf16 v[4:7], v[172:175], v[206:209], v[4:7]
	v_mfma_f32_16x16x32_bf16 v[18:21], v[176:179], v[180:183], v[18:21]
	v_mfma_f32_16x16x32_bf16 v[22:25], v[176:179], v[184:187], v[22:25]
	v_mfma_f32_16x16x32_bf16 v[26:29], v[176:179], v[188:191], v[26:29]
	v_mfma_f32_16x16x32_bf16 v[0:3], v[176:179], v[206:209], v[0:3]
	ds_read_b128 v[164:167], v16 offset:128
	ds_read_b128 v[168:171], v16 offset:4736
	ds_read_b128 v[172:175], v16 offset:18560
	ds_read_b128 v[176:179], v16 offset:23168
	ds_read_b128 v[180:183], v17 offset:55424
	ds_read_b128 v[184:187], v17 offset:60032
	ds_read_b128 v[188:191], v17 offset:64640
	ds_read_b128 v[206:209], v151 offset:64640
	s_waitcnt lgkmcnt(3)
	v_mfma_f32_16x16x32_bf16 v[34:37], v[164:167], v[180:183], v[34:37]
	s_waitcnt lgkmcnt(2)
	v_mfma_f32_16x16x32_bf16 v[38:41], v[164:167], v[184:187], v[38:41]
	s_waitcnt lgkmcnt(1)
	v_mfma_f32_16x16x32_bf16 v[42:45], v[164:167], v[188:191], v[42:45]
	s_waitcnt lgkmcnt(0)
	v_mfma_f32_16x16x32_bf16 v[12:15], v[164:167], v[206:209], v[12:15]
	v_mfma_f32_16x16x32_bf16 v[164:167], v[168:171], v[180:183], v[30:33]
	v_mfma_f32_16x16x32_bf16 v[210:213], v[168:171], v[184:187], v[46:49]
	v_mfma_f32_16x16x32_bf16 v[234:237], v[168:171], v[188:191], v[50:53]
	v_mfma_f32_16x16x32_bf16 v[168:171], v[168:171], v[206:209], v[8:11]
	v_mfma_f32_16x16x32_bf16 v[52:55], v[172:175], v[180:183], v[54:57]
	v_mfma_f32_16x16x32_bf16 v[238:241], v[172:175], v[184:187], v[58:61]
	v_mfma_f32_16x16x32_bf16 v[160:163], v[172:175], v[188:191], v[160:163]
	v_mfma_f32_16x16x32_bf16 v[4:7], v[172:175], v[206:209], v[4:7]
	v_mfma_f32_16x16x32_bf16 v[172:175], v[176:179], v[180:183], v[18:21]
	v_mfma_f32_16x16x32_bf16 v[20:23], v[176:179], v[184:187], v[22:25]
	v_mfma_f32_16x16x32_bf16 v[180:183], v[176:179], v[188:191], v[26:29]
	v_mfma_f32_16x16x32_bf16 v[176:179], v[176:179], v[206:209], v[0:3]
	s_nop 2
	ds_read_b128 v[0:3], v16 offset:192
	ds_read_b128 v[28:31], v16 offset:4800
	ds_read_b128 v[184:187], v16 offset:18624
	ds_read_b128 v[188:191], v16 offset:23232
	ds_read_b128 v[206:209], v17 offset:55488
	ds_read_b128 v[242:245], v17 offset:60096
	ds_read_b128 v[246:249], v17 offset:64704
	ds_read_b128 v[198:201], v151 offset:64704
	s_waitcnt lgkmcnt(0)
	s_barrier
	v_mfma_f32_16x16x32_bf16 v[48:51], v[0:3], v[242:245], v[38:41]
	v_mfma_f32_16x16x32_bf16 v[40:43], v[0:3], v[246:249], v[42:45]
	v_mfma_f32_16x16x32_bf16 v[44:47], v[184:187], v[246:249], v[160:163]
	s_nop 2
	global_load_dwordx2 v[160:161], v[64:65], off
	v_mfma_f32_16x16x32_bf16 v[60:63], v[184:187], v[206:209], v[52:55]
	v_mfma_f32_16x16x32_bf16 v[56:59], v[0:3], v[206:209], v[34:37]
	v_mfma_f32_16x16x32_bf16 v[52:55], v[184:187], v[242:245], v[238:241]
	s_waitcnt vmcnt(0)
	s_nop 4
	v_mul_f32_e32 v162, v60, v161
	v_fmac_f32_e32 v162, v56, v160
	v_mul_f32_e32 v56, v56, v161
	v_fma_f32 v56, v60, v160, -v56
	global_load_dwordx2 v[160:161], v[66:67], off
	v_bfe_u32 v163, v162, 16, 1
	v_bfe_u32 v60, v56, 16, 1
	v_add3_u32 v162, v162, v163, s70
	v_add_u32_e32 v163, v136, v137
	v_add3_u32 v56, v56, v60, s70
	ds_write_b16_d16_hi v163, v56 offset:55424
	v_mfma_f32_16x16x32_bf16 v[36:39], v[184:187], v[198:201], v[4:7]
	ds_write_b16_d16_hi v163, v162 offset:55296
	s_waitcnt vmcnt(0)
	v_mul_f32_e32 v56, v61, v161
	v_fmac_f32_e32 v56, v57, v160
	v_bfe_u32 v60, v56, 16, 1
	v_add3_u32 v56, v56, v60, s70
	ds_write_b16_d16_hi v163, v56 offset:55584
	v_mul_f32_e32 v56, v57, v161
	v_fma_f32 v56, v61, v160, -v56
	v_bfe_u32 v57, v56, 16, 1
	v_add3_u32 v56, v56, v57, s70
	ds_write_b16_d16_hi v163, v56 offset:55712
	global_load_dwordx2 v[56:57], v[68:69], off
	v_mfma_f32_16x16x32_bf16 v[32:35], v[0:3], v[198:201], v[12:15]
	s_waitcnt vmcnt(0)
	v_mul_f32_e32 v60, v62, v57
	v_mul_f32_e32 v57, v58, v57
	v_fmac_f32_e32 v60, v58, v56
	v_fma_f32 v56, v62, v56, -v57
	v_bfe_u32 v57, v56, 16, 1
	v_add3_u32 v56, v56, v57, s70
	ds_write_b16_d16_hi v163, v56 offset:56000
	global_load_dwordx2 v[56:57], v[70:71], off
	v_bfe_u32 v61, v60, 16, 1
	v_add3_u32 v60, v60, v61, s70
	ds_write_b16_d16_hi v163, v60 offset:55872
	v_mfma_f32_16x16x32_bf16 v[24:27], v[28:31], v[206:209], v[164:167]
	s_waitcnt vmcnt(0)
	v_mul_f32_e32 v58, v63, v57
	v_mul_f32_e32 v57, v59, v57
	v_fmac_f32_e32 v58, v59, v56
	v_fma_f32 v56, v63, v56, -v57
	v_bfe_u32 v57, v56, 16, 1
	v_add3_u32 v56, v56, v57, s70
	ds_write_b16_d16_hi v163, v56 offset:56288
	global_load_dwordx2 v[56:57], v[72:73], off
	v_bfe_u32 v60, v58, 16, 1
	v_add3_u32 v58, v58, v60, s70
	ds_write_b16_d16_hi v163, v58 offset:56160
	v_mfma_f32_16x16x32_bf16 v[16:19], v[28:31], v[242:245], v[210:213]
	s_waitcnt vmcnt(0)
	v_mul_f32_e32 v58, v52, v57
	v_fmac_f32_e32 v58, v48, v56
	v_mul_f32_e32 v48, v48, v57
	v_fma_f32 v48, v52, v56, -v48
	global_load_dwordx2 v[56:57], v[74:75], off
	v_bfe_u32 v59, v58, 16, 1
	v_bfe_u32 v52, v48, 16, 1
	v_add3_u32 v58, v58, v59, s70
	v_add_u32_e32 v59, v138, v137
	v_add3_u32 v48, v48, v52, s70
	ds_write_b16_d16_hi v59, v48 offset:55424
	v_mfma_f32_16x16x32_bf16 v[8:11], v[28:31], v[246:249], v[234:237]
	ds_write_b16_d16_hi v59, v58 offset:55296
	s_waitcnt vmcnt(0)
	v_mul_f32_e32 v48, v53, v57
	v_fmac_f32_e32 v48, v49, v56
	v_bfe_u32 v52, v48, 16, 1
	v_add3_u32 v48, v48, v52, s70
	ds_write_b16_d16_hi v59, v48 offset:55584
	v_mul_f32_e32 v48, v49, v57
	v_fma_f32 v48, v53, v56, -v48
	v_bfe_u32 v49, v48, 16, 1
	v_add3_u32 v48, v48, v49, s70
	ds_write_b16_d16_hi v59, v48 offset:55712
	global_load_dwordx2 v[48:49], v[76:77], off
	v_mfma_f32_16x16x32_bf16 v[0:3], v[28:31], v[198:201], v[168:171]
	s_waitcnt vmcnt(0)
	v_mul_f32_e32 v52, v54, v49
	v_mul_f32_e32 v49, v50, v49
	v_fmac_f32_e32 v52, v50, v48
	v_fma_f32 v48, v54, v48, -v49
	v_bfe_u32 v49, v48, 16, 1
	v_add3_u32 v48, v48, v49, s70
	ds_write_b16_d16_hi v59, v48 offset:56000
	global_load_dwordx2 v[48:49], v[78:79], off
	v_bfe_u32 v53, v52, 16, 1
	v_add3_u32 v52, v52, v53, s70
	ds_write_b16_d16_hi v59, v52 offset:55872
	v_mfma_f32_16x16x32_bf16 v[28:31], v[188:191], v[206:209], v[172:175]
	s_waitcnt vmcnt(0)
	v_mul_f32_e32 v50, v55, v49
	v_mul_f32_e32 v49, v51, v49
	v_fmac_f32_e32 v50, v51, v48
	v_fma_f32 v48, v55, v48, -v49
	v_bfe_u32 v49, v48, 16, 1
	v_add3_u32 v48, v48, v49, s70
	ds_write_b16_d16_hi v59, v48 offset:56288
	global_load_dwordx2 v[48:49], v[80:81], off
	v_bfe_u32 v52, v50, 16, 1
	v_add3_u32 v50, v50, v52, s70
	ds_write_b16_d16_hi v59, v50 offset:56160
	v_mfma_f32_16x16x32_bf16 v[20:23], v[188:191], v[242:245], v[20:23]
	s_waitcnt vmcnt(0)
	v_mul_f32_e32 v50, v44, v49
	v_fmac_f32_e32 v50, v40, v48
	v_mul_f32_e32 v40, v40, v49
	v_fma_f32 v40, v44, v48, -v40
	global_load_dwordx2 v[48:49], v[82:83], off
	v_bfe_u32 v51, v50, 16, 1
	v_bfe_u32 v44, v40, 16, 1
	v_add3_u32 v50, v50, v51, s70
	v_add_u32_e32 v51, v139, v137
	v_add3_u32 v40, v40, v44, s70
	ds_write_b16_d16_hi v51, v40 offset:55424
	ds_write_b16_d16_hi v51, v50 offset:55296
	v_mfma_f32_16x16x32_bf16 v[12:15], v[188:191], v[246:249], v[180:183]
	s_waitcnt vmcnt(0)
	v_mul_f32_e32 v40, v45, v49
	v_fmac_f32_e32 v40, v41, v48
	v_bfe_u32 v44, v40, 16, 1
	v_add3_u32 v40, v40, v44, s70
	ds_write_b16_d16_hi v51, v40 offset:55584
	v_mul_f32_e32 v40, v41, v49
	v_fma_f32 v40, v45, v48, -v40
	v_bfe_u32 v41, v40, 16, 1
	v_add3_u32 v40, v40, v41, s70
	ds_write_b16_d16_hi v51, v40 offset:55712
	global_load_dwordx2 v[40:41], v[84:85], off
	v_mfma_f32_16x16x32_bf16 v[4:7], v[188:191], v[198:201], v[176:179]
	s_waitcnt vmcnt(0)
	v_mul_f32_e32 v44, v46, v41
	v_mul_f32_e32 v41, v42, v41
	v_fmac_f32_e32 v44, v42, v40
	v_fma_f32 v40, v46, v40, -v41
	v_bfe_u32 v41, v40, 16, 1
	v_add3_u32 v40, v40, v41, s70
	ds_write_b16_d16_hi v51, v40 offset:56000
	global_load_dwordx2 v[40:41], v[86:87], off
	v_bfe_u32 v45, v44, 16, 1
	v_add3_u32 v44, v44, v45, s70
	ds_write_b16_d16_hi v51, v44 offset:55872
	s_waitcnt vmcnt(0)
	v_mul_f32_e32 v42, v47, v41
	v_mul_f32_e32 v41, v43, v41
	v_fmac_f32_e32 v42, v43, v40
	v_fma_f32 v40, v47, v40, -v41
	v_bfe_u32 v41, v40, 16, 1
	v_add3_u32 v40, v40, v41, s70
	ds_write_b16_d16_hi v51, v40 offset:56288
	global_load_dwordx2 v[40:41], v[88:89], off
	v_bfe_u32 v44, v42, 16, 1
	v_add3_u32 v42, v42, v44, s70
	ds_write_b16_d16_hi v51, v42 offset:56160
	s_waitcnt vmcnt(0)
	v_mul_f32_e32 v42, v36, v41
	v_fmac_f32_e32 v42, v32, v40
	v_mul_f32_e32 v32, v32, v41
	v_fma_f32 v32, v36, v40, -v32
	global_load_dwordx2 v[40:41], v[90:91], off
	v_bfe_u32 v43, v42, 16, 1
	v_bfe_u32 v36, v32, 16, 1
	v_add3_u32 v42, v42, v43, s70
	v_add_u32_e32 v43, v140, v137
	v_add3_u32 v32, v32, v36, s70
	ds_write_b16_d16_hi v43, v32 offset:55424
	ds_write_b16_d16_hi v43, v42 offset:55296
	s_waitcnt vmcnt(0)
	v_mul_f32_e32 v32, v37, v41
	v_fmac_f32_e32 v32, v33, v40
	v_bfe_u32 v36, v32, 16, 1
	v_add3_u32 v32, v32, v36, s70
	ds_write_b16_d16_hi v43, v32 offset:55584
	v_mul_f32_e32 v32, v33, v41
	v_fma_f32 v32, v37, v40, -v32
	v_bfe_u32 v33, v32, 16, 1
	v_add3_u32 v32, v32, v33, s70
	ds_write_b16_d16_hi v43, v32 offset:55712
	global_load_dwordx2 v[32:33], v[92:93], off
	s_waitcnt vmcnt(0)
	v_mul_f32_e32 v36, v38, v33
	v_mul_f32_e32 v33, v34, v33
	v_fmac_f32_e32 v36, v34, v32
	v_fma_f32 v32, v38, v32, -v33
	v_bfe_u32 v33, v32, 16, 1
	v_add3_u32 v32, v32, v33, s70
	ds_write_b16_d16_hi v43, v32 offset:56000
	global_load_dwordx2 v[32:33], v[94:95], off
	v_bfe_u32 v37, v36, 16, 1
	v_add3_u32 v36, v36, v37, s70
	ds_write_b16_d16_hi v43, v36 offset:55872
	s_waitcnt vmcnt(0)
	v_mul_f32_e32 v34, v39, v33
	v_mul_f32_e32 v33, v35, v33
	v_fmac_f32_e32 v34, v35, v32
	v_fma_f32 v32, v39, v32, -v33
	v_bfe_u32 v33, v32, 16, 1
	v_add3_u32 v32, v32, v33, s70
	ds_write_b16_d16_hi v43, v32 offset:56288
	global_load_dwordx2 v[32:33], v[96:97], off
	v_bfe_u32 v36, v34, 16, 1
	v_add3_u32 v34, v34, v36, s70
	ds_write_b16_d16_hi v43, v34 offset:56160
	s_waitcnt vmcnt(0)
	v_mul_f32_e32 v34, v28, v33
	v_fmac_f32_e32 v34, v24, v32
	v_mul_f32_e32 v24, v24, v33
	v_fma_f32 v24, v28, v32, -v24
	global_load_dwordx2 v[32:33], v[98:99], off
	v_bfe_u32 v35, v34, 16, 1
	v_bfe_u32 v28, v24, 16, 1
	v_add3_u32 v34, v34, v35, s70
	v_add_u32_e32 v35, v136, v141
	v_add3_u32 v24, v24, v28, s70
	ds_write_b16_d16_hi v35, v24 offset:55424
	ds_write_b16_d16_hi v35, v34 offset:55296
	s_waitcnt vmcnt(0)
	v_mul_f32_e32 v24, v29, v33
	v_fmac_f32_e32 v24, v25, v32
	v_bfe_u32 v28, v24, 16, 1
	v_add3_u32 v24, v24, v28, s70
	ds_write_b16_d16_hi v35, v24 offset:55584
	v_mul_f32_e32 v24, v25, v33
	v_fma_f32 v24, v29, v32, -v24
	v_bfe_u32 v25, v24, 16, 1
	v_add3_u32 v24, v24, v25, s70
	ds_write_b16_d16_hi v35, v24 offset:55712
	global_load_dwordx2 v[24:25], v[100:101], off
	s_waitcnt vmcnt(0)
	v_mul_f32_e32 v28, v30, v25
	v_mul_f32_e32 v25, v26, v25
	v_fmac_f32_e32 v28, v26, v24
	v_fma_f32 v24, v30, v24, -v25
	v_bfe_u32 v25, v24, 16, 1
	v_add3_u32 v24, v24, v25, s70
	ds_write_b16_d16_hi v35, v24 offset:56000
	global_load_dwordx2 v[24:25], v[102:103], off
	v_bfe_u32 v29, v28, 16, 1
	v_add3_u32 v28, v28, v29, s70
	ds_write_b16_d16_hi v35, v28 offset:55872
	s_waitcnt vmcnt(0)
	v_mul_f32_e32 v26, v31, v25
	v_mul_f32_e32 v25, v27, v25
	v_fmac_f32_e32 v26, v27, v24
	v_fma_f32 v24, v31, v24, -v25
	v_bfe_u32 v25, v24, 16, 1
	v_add3_u32 v24, v24, v25, s70
	ds_write_b16_d16_hi v35, v24 offset:56288
	global_load_dwordx2 v[24:25], v[104:105], off
	v_bfe_u32 v28, v26, 16, 1
	v_add3_u32 v26, v26, v28, s70
	ds_write_b16_d16_hi v35, v26 offset:56160
	s_waitcnt vmcnt(0)
	v_mul_f32_e32 v26, v20, v25
	v_fmac_f32_e32 v26, v16, v24
	v_mul_f32_e32 v16, v16, v25
	v_fma_f32 v16, v20, v24, -v16
	global_load_dwordx2 v[24:25], v[106:107], off
	v_bfe_u32 v27, v26, 16, 1
	v_bfe_u32 v20, v16, 16, 1
	v_add3_u32 v26, v26, v27, s70
	v_add_u32_e32 v27, v138, v141
	v_add3_u32 v16, v16, v20, s70
	ds_write_b16_d16_hi v27, v16 offset:55424
	ds_write_b16_d16_hi v27, v26 offset:55296
	s_waitcnt vmcnt(0)
	v_mul_f32_e32 v16, v21, v25
	v_fmac_f32_e32 v16, v17, v24
	v_bfe_u32 v20, v16, 16, 1
	v_add3_u32 v16, v16, v20, s70
	ds_write_b16_d16_hi v27, v16 offset:55584
	v_mul_f32_e32 v16, v17, v25
	v_fma_f32 v16, v21, v24, -v16
	v_bfe_u32 v17, v16, 16, 1
	v_add3_u32 v16, v16, v17, s70
	ds_write_b16_d16_hi v27, v16 offset:55712
	global_load_dwordx2 v[16:17], v[108:109], off
	s_waitcnt vmcnt(0)
	v_mul_f32_e32 v20, v22, v17
	v_mul_f32_e32 v17, v18, v17
	v_fmac_f32_e32 v20, v18, v16
	v_fma_f32 v16, v22, v16, -v17
	v_bfe_u32 v17, v16, 16, 1
	v_add3_u32 v16, v16, v17, s70
	ds_write_b16_d16_hi v27, v16 offset:56000
	global_load_dwordx2 v[16:17], v[110:111], off
	v_bfe_u32 v21, v20, 16, 1
	v_add3_u32 v20, v20, v21, s70
	ds_write_b16_d16_hi v27, v20 offset:55872
	s_waitcnt vmcnt(0)
	v_mul_f32_e32 v18, v23, v17
	v_mul_f32_e32 v17, v19, v17
	v_fmac_f32_e32 v18, v19, v16
	v_fma_f32 v16, v23, v16, -v17
	v_bfe_u32 v17, v16, 16, 1
	v_add3_u32 v16, v16, v17, s70
	ds_write_b16_d16_hi v27, v16 offset:56288
	global_load_dwordx2 v[16:17], v[114:115], off
	v_bfe_u32 v20, v18, 16, 1
	v_add3_u32 v18, v18, v20, s70
	ds_write_b16_d16_hi v27, v18 offset:56160
	s_waitcnt vmcnt(0)
	v_mul_f32_e32 v18, v12, v17
	v_fmac_f32_e32 v18, v8, v16
	v_mul_f32_e32 v8, v8, v17
	v_fma_f32 v8, v12, v16, -v8
	global_load_dwordx2 v[16:17], v[116:117], off
	v_bfe_u32 v19, v18, 16, 1
	v_bfe_u32 v12, v8, 16, 1
	v_add3_u32 v18, v18, v19, s70
	v_add_u32_e32 v19, v139, v141
	v_add3_u32 v8, v8, v12, s70
	ds_write_b16_d16_hi v19, v8 offset:55424
	ds_write_b16_d16_hi v19, v18 offset:55296
	s_waitcnt vmcnt(0)
	v_mul_f32_e32 v8, v13, v17
	v_fmac_f32_e32 v8, v9, v16
	v_bfe_u32 v12, v8, 16, 1
	v_add3_u32 v8, v8, v12, s70
	ds_write_b16_d16_hi v19, v8 offset:55584
	v_mul_f32_e32 v8, v9, v17
	v_fma_f32 v8, v13, v16, -v8
	v_bfe_u32 v9, v8, 16, 1
	v_add3_u32 v8, v8, v9, s70
	ds_write_b16_d16_hi v19, v8 offset:55712
	global_load_dwordx2 v[8:9], v[118:119], off
	s_waitcnt vmcnt(0)
	v_mul_f32_e32 v12, v14, v9
	v_mul_f32_e32 v9, v10, v9
	v_fmac_f32_e32 v12, v10, v8
	v_fma_f32 v8, v14, v8, -v9
	v_bfe_u32 v9, v8, 16, 1
	v_add3_u32 v8, v8, v9, s70
	ds_write_b16_d16_hi v19, v8 offset:56000
	global_load_dwordx2 v[8:9], v[120:121], off
	v_bfe_u32 v13, v12, 16, 1
	v_add3_u32 v12, v12, v13, s70
	ds_write_b16_d16_hi v19, v12 offset:55872
	s_waitcnt vmcnt(0)
	v_mul_f32_e32 v10, v15, v9
	v_mul_f32_e32 v9, v11, v9
	v_fmac_f32_e32 v10, v11, v8
	v_fma_f32 v8, v15, v8, -v9
	v_bfe_u32 v9, v8, 16, 1
	v_add3_u32 v8, v8, v9, s70
	ds_write_b16_d16_hi v19, v8 offset:56288
	global_load_dwordx2 v[8:9], v[122:123], off
	v_bfe_u32 v12, v10, 16, 1
	v_add3_u32 v10, v10, v12, s70
	ds_write_b16_d16_hi v19, v10 offset:56160
	s_waitcnt vmcnt(0)
	v_mul_f32_e32 v10, v4, v9
	v_fmac_f32_e32 v10, v0, v8
	v_mul_f32_e32 v0, v0, v9
	v_fma_f32 v0, v4, v8, -v0
	global_load_dwordx2 v[8:9], v[124:125], off
	v_bfe_u32 v11, v10, 16, 1
	v_bfe_u32 v4, v0, 16, 1
	v_add3_u32 v10, v10, v11, s70
	v_add_u32_e32 v11, v140, v141
	v_add3_u32 v0, v0, v4, s70
	ds_write_b16_d16_hi v11, v0 offset:55424
	ds_write_b16_d16_hi v11, v10 offset:55296
	s_waitcnt vmcnt(0)
	v_mul_f32_e32 v0, v5, v9
	v_fmac_f32_e32 v0, v1, v8
	v_bfe_u32 v4, v0, 16, 1
	v_add3_u32 v0, v0, v4, s70
	ds_write_b16_d16_hi v11, v0 offset:55584
	v_mul_f32_e32 v0, v1, v9
	v_fma_f32 v0, v5, v8, -v0
	v_bfe_u32 v1, v0, 16, 1
	v_add3_u32 v0, v0, v1, s70
	ds_write_b16_d16_hi v11, v0 offset:55712
	global_load_dwordx2 v[0:1], v[126:127], off
	v_add_u32_e32 v8, v133, v134
	v_add_u32_e32 v9, v132, v135
	s_waitcnt vmcnt(0)
	v_mul_f32_e32 v4, v6, v1
	v_mul_f32_e32 v1, v2, v1
	v_fmac_f32_e32 v4, v2, v0
	v_fma_f32 v0, v6, v0, -v1
	v_bfe_u32 v1, v0, 16, 1
	v_add3_u32 v0, v0, v1, s70
	ds_write_b16_d16_hi v11, v0 offset:56000
	global_load_dwordx2 v[0:1], v[128:129], off
	v_bfe_u32 v5, v4, 16, 1
	v_add3_u32 v4, v4, v5, s70
	ds_write_b16_d16_hi v11, v4 offset:55872
	s_waitcnt vmcnt(0)
	v_mul_f32_e32 v2, v7, v1
	v_mul_f32_e32 v1, v3, v1
	v_fmac_f32_e32 v2, v3, v0
	v_fma_f32 v0, v7, v0, -v1
	v_bfe_u32 v4, v2, 16, 1
	v_bfe_u32 v1, v0, 16, 1
	v_add3_u32 v2, v2, v4, s70
	v_add3_u32 v0, v0, v1, s70
	ds_write_b16_d16_hi v11, v2 offset:56160
	ds_write_b16_d16_hi v11, v0 offset:56288
	s_waitcnt lgkmcnt(0)
	s_barrier
	ds_read_b128 v[4:7], v8 offset:55296
	ds_read_b128 v[0:3], v8 offset:59904
	ds_read_b128 v[10:13], v9 offset:36864
	ds_read_b128 v[14:17], v9 offset:41472
	ds_read_b128 v[18:21], v9 offset:46080
	ds_read_b128 v[22:25], v9 offset:50688
	s_waitcnt lgkmcnt(3)
	v_mfma_f32_16x16x32_bf16 v[26:29], v[4:7], v[10:13], 0
	s_waitcnt lgkmcnt(2)
	v_mfma_f32_16x16x32_bf16 v[30:33], v[4:7], v[14:17], 0
	s_waitcnt lgkmcnt(1)
	v_mfma_f32_16x16x32_bf16 v[34:37], v[4:7], v[18:21], 0
	s_waitcnt lgkmcnt(0)
	v_mfma_f32_16x16x32_bf16 v[4:7], v[4:7], v[22:25], 0
	v_mfma_f32_16x16x32_bf16 v[10:13], v[0:3], v[10:13], 0
	v_mfma_f32_16x16x32_bf16 v[14:17], v[0:3], v[14:17], 0
	v_mfma_f32_16x16x32_bf16 v[18:21], v[0:3], v[18:21], 0
	v_mfma_f32_16x16x32_bf16 v[0:3], v[0:3], v[22:25], 0
	ds_read_b128 v[22:25], v8 offset:55360
	ds_read_b128 v[38:41], v8 offset:59968
	ds_read_b128 v[42:45], v9 offset:36928
	ds_read_b128 v[46:49], v9 offset:41536
	ds_read_b128 v[50:53], v9 offset:46144
	ds_read_b128 v[54:57], v9 offset:50752
	s_waitcnt lgkmcnt(3)
	v_mfma_f32_16x16x32_bf16 v[26:29], v[22:25], v[42:45], v[26:29]
	s_waitcnt lgkmcnt(2)
	v_mfma_f32_16x16x32_bf16 v[30:33], v[22:25], v[46:49], v[30:33]
	s_waitcnt lgkmcnt(1)
	v_mfma_f32_16x16x32_bf16 v[34:37], v[22:25], v[50:53], v[34:37]
	s_waitcnt lgkmcnt(0)
	v_mfma_f32_16x16x32_bf16 v[4:7], v[22:25], v[54:57], v[4:7]
	v_mfma_f32_16x16x32_bf16 v[10:13], v[38:41], v[42:45], v[10:13]
	v_mfma_f32_16x16x32_bf16 v[14:17], v[38:41], v[46:49], v[14:17]
	v_mfma_f32_16x16x32_bf16 v[18:21], v[38:41], v[50:53], v[18:21]
	v_mfma_f32_16x16x32_bf16 v[0:3], v[38:41], v[54:57], v[0:3]
	ds_read_b128 v[22:25], v8 offset:55424
	ds_read_b128 v[38:41], v8 offset:60032
	ds_read_b128 v[42:45], v9 offset:36992
	ds_read_b128 v[46:49], v9 offset:41600
	ds_read_b128 v[50:53], v9 offset:46208
	ds_read_b128 v[54:57], v9 offset:50816
	s_waitcnt lgkmcnt(3)
	v_mfma_f32_16x16x32_bf16 v[26:29], v[22:25], v[42:45], v[26:29]
	s_waitcnt lgkmcnt(2)
	v_mfma_f32_16x16x32_bf16 v[30:33], v[22:25], v[46:49], v[30:33]
	s_waitcnt lgkmcnt(1)
	v_mfma_f32_16x16x32_bf16 v[34:37], v[22:25], v[50:53], v[34:37]
	s_waitcnt lgkmcnt(0)
	v_mfma_f32_16x16x32_bf16 v[4:7], v[22:25], v[54:57], v[4:7]
	v_mfma_f32_16x16x32_bf16 v[10:13], v[38:41], v[42:45], v[10:13]
	v_mfma_f32_16x16x32_bf16 v[14:17], v[38:41], v[46:49], v[14:17]
	v_mfma_f32_16x16x32_bf16 v[18:21], v[38:41], v[50:53], v[18:21]
	v_mfma_f32_16x16x32_bf16 v[0:3], v[38:41], v[54:57], v[0:3]
	ds_read_b128 v[22:25], v8 offset:55488
	ds_read_b128 v[38:41], v8 offset:60096
	ds_read_b128 v[42:45], v9 offset:37056
	ds_read_b128 v[46:49], v9 offset:41664
	ds_read_b128 v[50:53], v9 offset:46272
	ds_read_b128 v[54:57], v9 offset:50880
	s_waitcnt lgkmcnt(0)
	s_barrier
	v_mfma_f32_16x16x32_bf16 v[26:29], v[22:25], v[42:45], v[26:29]
	v_mfma_f32_16x16x32_bf16 v[8:11], v[38:41], v[42:45], v[10:13]
	v_mfma_f32_16x16x32_bf16 v[12:15], v[38:41], v[46:49], v[14:17]
	v_mfma_f32_16x16x32_bf16 v[16:19], v[38:41], v[50:53], v[18:21]
	s_nop 4
	v_bfe_u32 v20, v26, 16, 1
	v_add3_u32 v20, v26, v20, s70
	ds_write_b16_d16_hi v142, v20 offset:55296
	v_bfe_u32 v20, v27, 16, 1
	v_add3_u32 v20, v27, v20, s70
	v_mfma_f32_16x16x32_bf16 v[30:33], v[22:25], v[46:49], v[30:33]
	ds_write_b16_d16_hi v142, v20 offset:55304
	v_bfe_u32 v20, v28, 16, 1
	v_add3_u32 v20, v28, v20, s70
	ds_write_b16_d16_hi v142, v20 offset:55312
	v_bfe_u32 v20, v29, 16, 1
	v_add3_u32 v20, v29, v20, s70
	ds_write_b16_d16_hi v142, v20 offset:55320
	s_nop 0
	v_bfe_u32 v20, v30, 16, 1
	v_add3_u32 v20, v30, v20, s70
	ds_write_b16_d16_hi v142, v20 offset:63488
	v_bfe_u32 v20, v31, 16, 1
	v_add3_u32 v20, v31, v20, s70
	v_mfma_f32_16x16x32_bf16 v[34:37], v[22:25], v[50:53], v[34:37]
	ds_write_b16_d16_hi v142, v20 offset:63496
	v_bfe_u32 v20, v32, 16, 1
	v_add3_u32 v20, v32, v20, s70
	ds_write_b16_d16_hi v142, v20 offset:63504
	v_bfe_u32 v20, v33, 16, 1
	v_add3_u32 v20, v33, v20, s70
	ds_write_b16_d16_hi v142, v20 offset:63512
	s_nop 0
	v_bfe_u32 v20, v34, 16, 1
	v_add3_u32 v20, v34, v20, s70
	ds_write_b16_d16_hi v143, v20 offset:16384
	v_bfe_u32 v20, v35, 16, 1
	v_add3_u32 v20, v35, v20, s70
	v_mfma_f32_16x16x32_bf16 v[4:7], v[22:25], v[54:57], v[4:7]
	ds_write_b16_d16_hi v143, v20 offset:16392
	v_bfe_u32 v20, v36, 16, 1
	v_add3_u32 v20, v36, v20, s70
	ds_write_b16_d16_hi v143, v20 offset:16400
	v_bfe_u32 v20, v37, 16, 1
	v_add3_u32 v20, v37, v20, s70
	ds_write_b16_d16_hi v143, v20 offset:16408
	s_nop 0
	v_bfe_u32 v20, v4, 16, 1
	v_add3_u32 v4, v4, v20, s70
	ds_write_b16_d16_hi v143, v4 offset:24576
	v_bfe_u32 v4, v5, 16, 1
	v_add3_u32 v4, v5, v4, s70
	ds_write_b16_d16_hi v143, v4 offset:24584
	v_bfe_u32 v4, v6, 16, 1
	v_add3_u32 v4, v6, v4, s70
	ds_write_b16_d16_hi v143, v4 offset:24592
	v_bfe_u32 v4, v7, 16, 1
	v_add3_u32 v4, v7, v4, s70
	ds_write_b16_d16_hi v143, v4 offset:24600
	v_bfe_u32 v4, v8, 16, 1
	v_add3_u32 v4, v8, v4, s70
	ds_write_b16_d16_hi v142, v4 offset:55424
	v_bfe_u32 v4, v9, 16, 1
	v_add3_u32 v4, v9, v4, s70
	ds_write_b16_d16_hi v142, v4 offset:55432
	v_bfe_u32 v4, v10, 16, 1
	v_add3_u32 v4, v10, v4, s70
	ds_write_b16_d16_hi v142, v4 offset:55440
	v_bfe_u32 v4, v11, 16, 1
	v_add3_u32 v4, v11, v4, s70
	ds_write_b16_d16_hi v142, v4 offset:55448
	v_bfe_u32 v4, v12, 16, 1
	v_add3_u32 v4, v12, v4, s70
	ds_write_b16_d16_hi v142, v4 offset:63616
	v_bfe_u32 v4, v13, 16, 1
	v_add3_u32 v4, v13, v4, s70
	ds_write_b16_d16_hi v142, v4 offset:63624
	v_bfe_u32 v4, v14, 16, 1
	v_add3_u32 v4, v14, v4, s70
	ds_write_b16_d16_hi v142, v4 offset:63632
	v_bfe_u32 v4, v15, 16, 1
	v_add3_u32 v4, v15, v4, s70
	ds_write_b16_d16_hi v142, v4 offset:63640
	v_bfe_u32 v4, v16, 16, 1
	v_add3_u32 v4, v16, v4, s70
	ds_write_b16_d16_hi v143, v4 offset:16512
	v_bfe_u32 v4, v17, 16, 1
	v_add3_u32 v4, v17, v4, s70
	v_mfma_f32_16x16x32_bf16 v[0:3], v[38:41], v[54:57], v[0:3]
	ds_write_b16_d16_hi v143, v4 offset:16520
	v_bfe_u32 v4, v18, 16, 1
	v_add3_u32 v4, v18, v4, s70
	ds_write_b16_d16_hi v143, v4 offset:16528
	v_bfe_u32 v4, v19, 16, 1
	v_add3_u32 v4, v19, v4, s70
	ds_write_b16_d16_hi v143, v4 offset:16536
	s_nop 0
	v_bfe_u32 v4, v0, 16, 1
	v_add3_u32 v0, v0, v4, s70
	ds_write_b16_d16_hi v143, v0 offset:24704
	v_bfe_u32 v0, v1, 16, 1
	v_add3_u32 v0, v1, v0, s70
	ds_write_b16_d16_hi v143, v0 offset:24712
	v_bfe_u32 v0, v2, 16, 1
	v_add3_u32 v0, v2, v0, s70
	ds_write_b16_d16_hi v143, v0 offset:24720
	v_bfe_u32 v0, v3, 16, 1
	v_add3_u32 v0, v3, v0, s70
	ds_write_b16_d16_hi v143, v0 offset:24728
	s_waitcnt lgkmcnt(0)
	s_barrier
	ds_read_b64 v[0:1], v152 offset:55296
	v_add_u32_e32 v2, s1, v130
	v_ashrrev_i32_e32 v3, 31, v2
	v_lshlrev_b64 v[2:3], 12, v[2:3]
	v_lshl_add_u64 v[2:3], s[16:17], 0, v[2:3]
	s_waitcnt lgkmcnt(0)
	global_store_dwordx2 v[2:3], v[0:1], off
	ds_read_b64 v[0:1], v153 offset:55296
	v_add_u32_e32 v2, s1, v144
	v_ashrrev_i32_e32 v3, 31, v2
	v_lshlrev_b64 v[2:3], 12, v[2:3]
	v_lshl_add_u64 v[2:3], s[16:17], 0, v[2:3]
	s_waitcnt lgkmcnt(0)
	global_store_dwordx2 v[2:3], v[0:1], off
	ds_read_b64 v[0:1], v154 offset:55296
	v_add_u32_e32 v2, s1, v145
	v_ashrrev_i32_e32 v3, 31, v2
	v_lshlrev_b64 v[2:3], 12, v[2:3]
	v_lshl_add_u64 v[2:3], s[16:17], 0, v[2:3]
	s_waitcnt lgkmcnt(0)
	global_store_dwordx2 v[2:3], v[0:1], off
	ds_read_b64 v[0:1], v155 offset:55296
	v_add_u32_e32 v2, s1, v146
	v_ashrrev_i32_e32 v3, 31, v2
	v_lshlrev_b64 v[2:3], 12, v[2:3]
	v_lshl_add_u64 v[2:3], s[16:17], 0, v[2:3]
	s_waitcnt lgkmcnt(0)
	global_store_dwordx2 v[2:3], v[0:1], off
	ds_read_b64 v[0:1], v156 offset:55296
	v_add_u32_e32 v2, s1, v147
	v_ashrrev_i32_e32 v3, 31, v2
	v_lshlrev_b64 v[2:3], 12, v[2:3]
	v_lshl_add_u64 v[2:3], s[16:17], 0, v[2:3]
	s_waitcnt lgkmcnt(0)
	global_store_dwordx2 v[2:3], v[0:1], off
	ds_read_b64 v[0:1], v157 offset:55296
	v_add_u32_e32 v2, s1, v148
	v_ashrrev_i32_e32 v3, 31, v2
	v_lshlrev_b64 v[2:3], 12, v[2:3]
	v_lshl_add_u64 v[2:3], s[16:17], 0, v[2:3]
	s_waitcnt lgkmcnt(0)
	global_store_dwordx2 v[2:3], v[0:1], off
	ds_read_b64 v[0:1], v158 offset:55296
	v_add_u32_e32 v2, s1, v149
	v_ashrrev_i32_e32 v3, 31, v2
	v_lshlrev_b64 v[2:3], 12, v[2:3]
	v_lshl_add_u64 v[2:3], s[16:17], 0, v[2:3]
	s_waitcnt lgkmcnt(0)
	global_store_dwordx2 v[2:3], v[0:1], off
	ds_read_b64 v[0:1], v159 offset:55296
	v_add_u32_e32 v2, s1, v150
	v_ashrrev_i32_e32 v3, 31, v2
	v_lshlrev_b64 v[2:3], 12, v[2:3]
	v_lshl_add_u64 v[2:3], s[16:17], 0, v[2:3]
	s_waitcnt lgkmcnt(0)
	global_store_dwordx2 v[2:3], v[0:1], off
	s_cbranch_scc1 .LBB1_480
	s_movk_i32 s25, 0x120
